# adaLN norm row loop (4 phases): each row's two result stores deferred until after the next row's loads are issued so the load wait no longer drains them, plus next-row cache-line touch loads
# baseline (speedup 1.0000x reference)
; __device__ __forceinline__ void st8(bf16_t* p, f32x4 a, f32x4 b) { u32x4 w; w.x = cvt_pk_bf16(a[0], a[1]); w.y = cvt_pk_bf16(a[2], a[3]); w.z = cvt_pk_bf16(b[0], b[1]); w.w = cvt_pk_bf16(b[2], b[3]); *(u32x4*)p = w; }
; template <class T>
; __device__ __forceinline__ void phase_norm(const T* xl, const T* xc, const float* nw, const float* mod  , int sh_off, int sc_off,
;                                            bf16u* HN, int skip_ctx, int lane, int wave, int G, const int bid) {
;     const int gw = bid * 8 + wave, NGW = G * 8; int cur = -1; f32x4 a[4], s[4];
;     for (int m = gw; m < MROWS; m += NGW) {
;         const int b = m / SEQU, j = m % SEQU; const bool isc = j < CTXL; if (isc && skip_ctx) continue;
;         const int wh = isc ? 2 : b; const T* src = isc ? xc + (size_t)(b * CTXL + j) * DM : xl + (size_t)(b * LSEQ + j - CTXL) * DM;
;         if (wh != cur) { cur = wh;
; #pragma unroll
;             for (int jj = 0; jj < 4; ++jj) { const int k = 8 * lane + 4 * (jj & 1) + 512 * (jj >> 1); const f32x4 w = *(const f32x4*)(nw + k), sc = *(const f32x4*)(mod + wh * NMODV + sc_off + k);
;                 a[jj] = w * (sc + 1.0f); s[jj] = *(const f32x4*)(mod + wh * NMODV + sh_off + k); } }
;         f32x4 v[4]; float ss = 0.f;
; #pragma unroll
;         for (int h = 0; h < 2; ++h) pg8::ld8(src + 8 * lane + 512 * h, v[2 * h], v[2 * h + 1]);
; #pragma unroll
;         for (int jj = 0; jj < 4; ++jj) ss += (v[jj].x * v[jj].x + v[jj].y * v[jj].y) + (v[jj].z * v[jj].z + v[jj].w * v[jj].w);
;         const float rstd = rsqrtf(wave_sum(ss, lane) * (1.0f / DM) + EPSN);
; #pragma unroll
;         for (int h = 0; h < 2; ++h) pg8::st8(HN + (size_t)m * DM + 8 * lane + 512 * h, (v[2 * h] * rstd) * a[2 * h] + s[2 * h], (v[2 * h + 1] * rstd) * a[2 * h + 1] + s[2 * h + 1]);
;     }
.LBB0_148:
	s_mov_b32 s100, 0
	s_cmp_lt_i32 s70, 3
	s_cselect_b64 s[2:3], -1, 0
	s_and_b64 s[2:3], s[2:3], s[0:1]
	s_andn2_b64 vcc, exec, s[2:3]
	s_cbranch_vccnz .LBB0_158
	s_mov_b32 s0, 0
	s_mov_b32 s6, s83
	v_mbcnt_lo_u32_b32 v0, -1, s0
	v_mbcnt_hi_u32_b32 v0, -1, v0
	v_add_u32_e32 v0, s86, v0
	s_mov_b32 s7, s84
	v_readfirstlane_b32 s0, v0
	s_ashr_i32 s10, s0, 6
	s_add_i32 s0, 0, 0x24800
	v_mov_b32_e32 v1, s0
	s_add_i32 s0, 0, 0x24810
	ds_read_b64 v[2:3], v1
	v_mov_b32_e32 v1, s0
	s_add_i32 s0, 0, 0x24820
	v_mov_b32_e32 v6, s0
	s_add_i32 s0, 0, 0x248c0
	v_mov_b32_e32 v8, s0
	ds_read_b64 v[4:5], v1
	ds_read_b64 v[6:7], v6
	ds_read_b64 v[8:9], v8
	s_lshl_b32 s6, s6, 3
	s_add_i32 s6, s10, s6
	s_mov_b32 s18, -1
	s_waitcnt lgkmcnt(3)
	v_readfirstlane_b32 s1, v3
	v_readfirstlane_b32 s0, v2
	s_waitcnt lgkmcnt(2)
	v_readfirstlane_b32 s5, v5
	v_readfirstlane_b32 s4, v4
	s_waitcnt lgkmcnt(1)
	v_readfirstlane_b32 s9, v7
	v_readfirstlane_b32 s8, v6
	s_waitcnt lgkmcnt(0)
	v_readfirstlane_b32 s11, v9
	s_cmp_gt_i32 s6, 0x81ff
	v_readfirstlane_b32 s10, v8
	s_cbranch_scc1 .LBB0_158
	v_and_b32_e32 v2, 63, v0
	s_add_u32 s14, s10, 0x3000000
	v_mov_b32_e32 v23, 0
	v_lshlrev_b32_e32 v0, 2, v2
	v_lshlrev_b32_e32 v22, 4, v2
	s_addc_u32 s15, s11, 0
	v_lshlrev_b32_e32 v16, 3, v2
	v_xor_b32_e32 v17, 4, v0
	v_xor_b32_e32 v38, 8, v0
	v_xor_b32_e32 v39, 16, v0
	v_xor_b32_e32 v40, 32, v0
	v_xor_b32_e32 v41, 64, v0
	v_xor_b32_e32 v42, 0x80, v0
	v_lshl_add_u64 v[0:1], s[10:11], 0, v[22:23]
	s_mov_b64 s[10:11], 0x3500000
	v_lshl_add_u64 v[18:19], v[0:1], 0, s[10:11]
	v_lshlrev_b32_e32 v22, 5, v2
	v_or_b32_e32 v0, 0x200, v16
	s_lshl_b32 s16, s7, 3
	v_lshl_add_u64 v[20:21], s[8:9], 0, v[22:23]
	v_mov_b32_e32 v22, v23
	v_mov_b32_e32 v24, v23
	v_mov_b32_e32 v25, v23
	v_mov_b32_e32 v32, v23
	v_mov_b32_e32 v33, v23
	v_mov_b32_e32 v26, v23
	v_mov_b32_e32 v27, v23
	v_mov_b32_e32 v34, v23
	v_mov_b32_e32 v35, v23
	v_mov_b32_e32 v28, v23
	v_mov_b32_e32 v29, v23
	v_mov_b32_e32 v36, v23
	v_mov_b32_e32 v37, v23
	v_mov_b32_e32 v30, v23
	v_mov_b32_e32 v31, v23
	v_lshlrev_b32_e32 v43, 2, v0
	v_mov_b32_e32 v44, 0x358637bd
	s_mov_b32 s17, 0x800000
	s_branch .LBB0_152
.LBB0_151:
	s_ashr_i32 s9, s8, 31
	s_lshl_b64 s[8:9], s[8:9], 12
	s_add_u32 s8, s10, s8
	s_addc_u32 s9, s11, s9
	global_load_dwordx4 v[46:49], v45, s[8:9]
	global_load_dwordx4 v[50:53], v45, s[8:9] offset:16
	global_load_dwordx4 v[54:57], v45, s[8:9] offset:2064
	global_load_dwordx4 v[58:61], v45, s[8:9] offset:2048
	s_cmp_eq_u32 s100, 0
	s_cbranch_scc1 .Lnorm2_first
	global_store_dwordx4 v[212:213], v[204:207], off
	global_store_dwordx4 v[212:213], v[208:211], off offset:1024
	s_branch .Lnorm2_join
.Lnorm2_first:
	global_load_dword v200, v45, s[8:9]
	global_load_dword v200, v45, s[8:9] offset:2048
.Lnorm2_join:
	s_ashr_i32 s7, s6, 31
	s_lshl_b64 s[8:9], s[6:7], 11
	s_add_i32 s6, s6, s16
	s_cmp_lt_i32 s6, 0x8200
	s_waitcnt vmcnt(5)
	v_pk_mul_f32 v[62:63], v[48:49], v[48:49]
	v_pk_mul_f32 v[64:65], v[46:47], v[46:47]
	s_waitcnt vmcnt(4)
	v_pk_mul_f32 v[66:67], v[52:53], v[52:53]
	v_pk_mul_f32 v[68:69], v[50:51], v[50:51]
	v_pk_mov_b32 v[74:75], v[64:65], v[62:63] op_sel:[1,0]
	v_mov_b32_e32 v65, v63
	v_pk_mov_b32 v[62:63], v[68:69], v[66:67] op_sel:[1,0]
	v_mov_b32_e32 v69, v67
	s_waitcnt vmcnt(3)
	v_mul_f32_e32 v73, v55, v55
	s_waitcnt vmcnt(2)
	v_mul_f32_e32 v70, v59, v59
	v_mul_f32_e32 v72, v61, v61
	v_pk_add_f32 v[64:65], v[74:75], v[64:65]
	v_pk_add_f32 v[62:63], v[62:63], v[68:69]
	v_mul_f32_e32 v45, v54, v54
	v_mul_f32_e32 v76, v56, v56
	v_mul_f32_e32 v77, v57, v57
	v_pk_fma_f32 v[66:67], v[58:59], v[58:59], v[70:71] op_sel_hi:[1,1,0]
	v_pk_fma_f32 v[70:71], v[60:61], v[60:61], v[72:73] op_sel_hi:[1,1,0]
	v_pk_add_f32 v[64:65], v[64:65], v[64:65] op_sel:[0,1] op_sel_hi:[1,0]
	v_pk_add_f32 v[62:63], v[62:63], v[62:63] op_sel:[0,1] op_sel_hi:[1,0]
	v_mov_b32_e32 v67, v76
	v_mov_b32_e32 v71, v77
	v_mov_b32_e32 v65, v45
	v_mov_b32_e32 v63, v73
	v_pk_add_f32 v[66:67], v[66:67], v[70:71]
	v_pk_add_f32 v[62:63], v[64:65], v[62:63]
	s_nop 0
	v_pk_add_f32 v[62:63], v[62:63], v[66:67]
	s_nop 0
	v_add_f32_e32 v45, v62, v63
	ds_bpermute_b32 v62, v17, v45
	s_waitcnt lgkmcnt(0)
	v_add_f32_e32 v45, v45, v62
	ds_bpermute_b32 v62, v38, v45
	s_waitcnt lgkmcnt(0)
	v_add_f32_e32 v45, v45, v62
	ds_bpermute_b32 v62, v39, v45
	s_waitcnt lgkmcnt(0)
	v_add_f32_e32 v45, v45, v62
	ds_bpermute_b32 v62, v40, v45
	s_waitcnt lgkmcnt(0)
	v_add_f32_e32 v45, v45, v62
	ds_bpermute_b32 v62, v41, v45
	s_waitcnt lgkmcnt(0)
	v_add_f32_e32 v45, v45, v62
	ds_bpermute_b32 v62, v42, v45
	s_waitcnt lgkmcnt(0)
	v_add_f32_e32 v45, v45, v62
	v_fmamk_f32 v45, v45, 0x3a800000, v44
	v_mul_f32_e32 v62, 0x4b800000, v45
	v_cmp_gt_f32_e32 vcc, s17, v45
	s_nop 1
	v_cndmask_b32_e32 v45, v45, v62, vcc
	v_rsq_f32_e32 v45, v45
	v_lshl_add_u64 v[62:63], v[18:19], 0, s[8:9]
	v_mul_f32_e32 v64, 0x45800000, v45
	v_cndmask_b32_e32 v64, v45, v64, vcc
	v_pk_mul_f32 v[46:47], v[46:47], v[64:65] op_sel_hi:[1,0]
	v_pk_mul_f32 v[48:49], v[48:49], v[64:65] op_sel_hi:[1,0]
	v_pk_mul_f32 v[50:51], v[50:51], v[64:65] op_sel_hi:[1,0]
	v_pk_mul_f32 v[52:53], v[52:53], v[64:65] op_sel_hi:[1,0]
	v_pk_fma_f32 v[48:49], v[24:25], v[48:49], v[14:15]
	v_pk_fma_f32 v[46:47], v[22:23], v[46:47], v[12:13]
	v_pk_mul_f32 v[58:59], v[58:59], v[64:65] op_sel_hi:[1,0]
	v_pk_mul_f32 v[60:61], v[60:61], v[64:65] op_sel_hi:[1,0]
	v_pk_mul_f32 v[54:55], v[54:55], v[64:65] op_sel_hi:[1,0]
	v_pk_mul_f32 v[56:57], v[56:57], v[64:65] op_sel_hi:[1,0]
	v_pk_fma_f32 v[52:53], v[26:27], v[52:53], v[6:7]
	v_pk_fma_f32 v[50:51], v[32:33], v[50:51], v[4:5]
	v_cvt_pk_bf16_f32 v46, v46, v47
	v_cvt_pk_bf16_f32 v47, v48, v49
	v_pk_fma_f32 v[60:61], v[28:29], v[60:61], v[10:11]
	v_cvt_pk_bf16_f32 v48, v50, v51
	v_cvt_pk_bf16_f32 v49, v52, v53
	v_pk_fma_f32 v[58:59], v[34:35], v[58:59], v[8:9]
	v_pk_fma_f32 v[56:57], v[30:31], v[56:57], v[2:3]
	v_pk_fma_f32 v[54:55], v[36:37], v[54:55], v[0:1]
	v_mov_b32_e32 v204, v46
	v_mov_b32_e32 v205, v47
	v_mov_b32_e32 v206, v48
	v_mov_b32_e32 v207, v49
	v_mov_b32_e32 v212, v62
	v_mov_b32_e32 v213, v63
	s_nop 1
	v_cvt_pk_bf16_f32 v46, v58, v59
	v_cvt_pk_bf16_f32 v47, v60, v61
	v_cvt_pk_bf16_f32 v48, v54, v55
	v_cvt_pk_bf16_f32 v49, v56, v57
	v_mov_b32_e32 v208, v46
	v_mov_b32_e32 v209, v47
	v_mov_b32_e32 v210, v48
	v_mov_b32_e32 v211, v49
	s_mov_b32 s100, 1
	s_cbranch_scc0 .LBB0_158

; __device__ __forceinline__ void st8(bf16_t* p, f32x4 a, f32x4 b) { u32x4 w; w.x = cvt_pk_bf16(a[0], a[1]); w.y = cvt_pk_bf16(a[2], a[3]); w.z = cvt_pk_bf16(b[0], b[1]); w.w = cvt_pk_bf16(b[2], b[3]); *(u32x4*)p = w; }
; template <class T>
; __device__ __forceinline__ void phase_norm(const T* xl, const T* xc, const float* nw, const float* mod  , int sh_off, int sc_off,
;                                            bf16u* HN, int skip_ctx, int lane, int wave, int G, const int bid) {
;     ...
;         for (int h = 0; h < 2; ++h) pg8::st8(HN + (size_t)m * DM + 8 * lane + 512 * h, (v[2 * h] * rstd) * a[2 * h] + s[2 * h], (v[2 * h + 1] * rstd) * a[2 * h + 1] + s[2 * h + 1]);
;     }
; }
.LBB0_158:
	s_cmp_eq_u32 s100, 0
	s_cbranch_scc1 .Lnorm2_done
	global_store_dwordx4 v[212:213], v[204:207], off
	global_store_dwordx4 v[212:213], v[208:211], off offset:1024

; __device__ __forceinline__ unsigned cvt_pk_bf16(float lo, float hi) { unsigned r; asm volatile("v_cvt_pk_bf16_f32 %0, %1, %2" : "=v"(r) : "v"(lo), "v"(hi)); return r; }
; __device__ __forceinline__ void ld8(const bf16_t* p, f32x4& a, f32x4& b) { const u32x4 r = *(const u32x4*)p;
;     a = (f32x4){__uint_as_float(r.x << 16), __uint_as_float(r.x & 0xffff0000u), __uint_as_float(r.y << 16), __uint_as_float(r.y & 0xffff0000u)};
;     b = (f32x4){__uint_as_float(r.z << 16), __uint_as_float(r.z & 0xffff0000u), __uint_as_float(r.w << 16), __uint_as_float(r.w & 0xffff0000u)}; }
; __device__ __forceinline__ void st8(bf16_t* p, f32x4 a, f32x4 b) { u32x4 w; w.x = cvt_pk_bf16(a[0], a[1]); w.y = cvt_pk_bf16(a[2], a[3]); w.z = cvt_pk_bf16(b[0], b[1]); w.w = cvt_pk_bf16(b[2], b[3]); *(u32x4*)p = w; }
; template <class T>
; __device__ __forceinline__ void phase_norm(const T* xl, const T* xc, const float* nw, const float* mod  , int sh_off, int sc_off,
;                                            bf16u* HN, int skip_ctx, int lane, int wave, int G, const int bid) {
;     ...
;     for (int m = gw; m < MROWS; m += NGW) {
;         const int b = m / SEQU, j = m % SEQU; const bool isc = j < CTXL; if (isc && skip_ctx) continue;
;         const int wh = isc ? 2 : b; const T* src = isc ? xc + (size_t)(b * CTXL + j) * DM : xl + (size_t)(b * LSEQ + j - CTXL) * DM;
;         if (wh != cur) { cur = wh;
; #pragma unroll
;             for (int jj = 0; jj < 4; ++jj) { const int k = 8 * lane + 4 * (jj & 1) + 512 * (jj >> 1); const f32x4 w = *(const f32x4*)(nw + k), sc = *(const f32x4*)(mod + wh * NMODV + sc_off + k);
;                 a[jj] = w * (sc + 1.0f); s[jj] = *(const f32x4*)(mod + wh * NMODV + sh_off + k); } }
;         f32x4 v[4]; float ss = 0.f;
; #pragma unroll
;         for (int h = 0; h < 2; ++h) pg8::ld8(src + 8 * lane + 512 * h, v[2 * h], v[2 * h + 1]);
; #pragma unroll
;         for (int jj = 0; jj < 4; ++jj) ss += (v[jj].x * v[jj].x + v[jj].y * v[jj].y) + (v[jj].z * v[jj].z + v[jj].w * v[jj].w);
;         const float rstd = rsqrtf(wave_sum(ss, lane) * (1.0f / DM) + EPSN);
; #pragma unroll
;         for (int h = 0; h < 2; ++h) pg8::st8(HN + (size_t)m * DM + 8 * lane + 512 * h, (v[2 * h] * rstd) * a[2 * h] + s[2 * h], (v[2 * h + 1] * rstd) * a[2 * h + 1] + s[2 * h + 1]);
;     }
.LBB0_735:
	s_mov_b32 s100, 0
	s_cmp_lt_i32 s70, 9
	s_cselect_b64 s[2:3], -1, 0
	s_and_b64 s[2:3], s[2:3], s[0:1]
	s_andn2_b64 vcc, exec, s[2:3]
	s_cbranch_vccnz .LBB0_745
	s_mov_b32 s0, 0
	s_add_i32 s1, 0, 0x24828
	s_waitcnt vmcnt(0)
	v_mbcnt_lo_u32_b32 v0, -1, s0
	v_mbcnt_hi_u32_b32 v0, -1, v0
	v_add_u32_e32 v0, s86, v0
	s_mov_b32 s0, s83
	s_mov_b32 s5, s84
	v_mov_b32_e32 v1, s1
	s_add_i32 s1, 0, 0x248c0
	ds_read_b64 v[2:3], v1
	v_mov_b32_e32 v1, s1
	ds_read_b64 v[4:5], v1
	v_readfirstlane_b32 s1, v0
	s_ashr_i32 s4, s1, 6
	s_lshl_b32 s0, s0, 3
	s_add_i32 s4, s4, s0
	s_mov_b32 s16, -1
	s_waitcnt lgkmcnt(1)
	v_readfirstlane_b32 s7, v3
	v_readfirstlane_b32 s6, v2
	s_waitcnt lgkmcnt(0)
	v_readfirstlane_b32 s1, v5
	s_cmp_gt_i32 s4, 0x81ff
	v_readfirstlane_b32 s0, v4
	s_cbranch_scc1 .LBB0_745
	v_and_b32_e32 v2, 63, v0
	v_mov_b32_e32 v23, 0
	v_lshlrev_b32_e32 v0, 2, v2
	v_lshlrev_b32_e32 v22, 4, v2
	v_lshlrev_b32_e32 v16, 3, v2
	v_xor_b32_e32 v17, 4, v0
	v_xor_b32_e32 v38, 8, v0
	v_xor_b32_e32 v39, 16, v0
	v_xor_b32_e32 v40, 32, v0
	v_xor_b32_e32 v41, 64, v0
	v_xor_b32_e32 v42, 0x80, v0
	v_lshl_add_u64 v[0:1], s[0:1], 0, v[22:23]
	s_mov_b64 s[8:9], 0x3500000
	s_add_u32 s12, s0, 0x3000000
	v_lshl_add_u64 v[18:19], v[0:1], 0, s[8:9]
	v_lshlrev_b32_e32 v22, 5, v2
	v_or_b32_e32 v0, 0x200, v16
	s_addc_u32 s13, s1, 0
	s_lshl_b32 s14, s5, 3
	v_lshl_add_u64 v[20:21], s[6:7], 0, v[22:23]
	v_mov_b32_e32 v22, v23
	v_mov_b32_e32 v24, v23
	v_mov_b32_e32 v25, v23
	v_mov_b32_e32 v32, v23
	v_mov_b32_e32 v33, v23
	v_mov_b32_e32 v26, v23
	v_mov_b32_e32 v27, v23
	v_mov_b32_e32 v34, v23
	v_mov_b32_e32 v35, v23
	v_mov_b32_e32 v28, v23
	v_mov_b32_e32 v29, v23
	v_mov_b32_e32 v36, v23
	v_mov_b32_e32 v37, v23
	v_mov_b32_e32 v30, v23
	v_mov_b32_e32 v31, v23
	v_lshlrev_b32_e32 v43, 2, v0
	v_mov_b32_e32 v44, 0x358637bd
	s_mov_b32 s15, 0x800000
	s_branch .LBB0_739
.LBB0_738:
	s_add_u32 s5, s0, s8
	s_addc_u32 s8, s1, s9
	s_ashr_i32 s7, s6, 31
	s_lshl_b64 s[6:7], s[6:7], 11
	s_add_u32 s6, s5, s6
	s_addc_u32 s7, s8, s7
	v_lshlrev_b32_e32 v45, 1, v16
	global_load_dwordx4 v[46:49], v45, s[6:7] offset:1024
	global_load_dwordx4 v[50:53], v45, s[6:7]
	s_lshl_b32 s98, s14, 11
	s_add_u32 s98, s6, s98
	s_addc_u32 s99, s7, 0
	s_cmp_eq_u32 s100, 0
	s_cbranch_scc1 .Lnorm8_first
	global_store_dwordx4 v[212:213], v[204:207], off
	global_store_dwordx4 v[212:213], v[208:211], off offset:1024
	s_branch .Lnorm8_join
.Lnorm8_first:
	global_load_dword v200, v45, s[6:7]
	global_load_dword v200, v45, s[6:7] offset:1024
.Lnorm8_join:
	global_load_dword v200, v45, s[98:99] offset:1024
	global_load_dword v200, v45, s[98:99]
	s_ashr_i32 s5, s4, 31
	s_lshl_b64 s[6:7], s[4:5], 11
	s_add_i32 s4, s4, s14
	s_cmp_lt_i32 s4, 0x8200
	s_waitcnt vmcnt(5)
	v_lshlrev_b32_e32 v54, 16, v48
	s_waitcnt vmcnt(4)
	v_lshlrev_b32_e32 v56, 16, v50
	v_and_b32_e32 v57, 0xffff0000, v50
	v_lshlrev_b32_e32 v50, 16, v51
	v_and_b32_e32 v51, 0xffff0000, v51
	v_lshlrev_b32_e32 v59, 16, v53
	v_lshlrev_b32_e32 v58, 16, v52
	v_and_b32_e32 v53, 0xffff0000, v53
	v_and_b32_e32 v52, 0xffff0000, v52
	v_mul_f32_e32 v62, v56, v56
	v_mul_f32_e32 v64, v50, v50
	v_lshlrev_b32_e32 v60, 16, v46
	v_and_b32_e32 v61, 0xffff0000, v46
	v_lshlrev_b32_e32 v46, 16, v47
	v_pk_mul_f32 v[66:67], v[52:53], v[52:53]
	v_pk_fma_f32 v[62:63], v[56:57], v[56:57], v[62:63] op_sel_hi:[1,1,0]
	v_pk_fma_f32 v[64:65], v[50:51], v[50:51], v[64:65] op_sel_hi:[1,1,0]
	v_and_b32_e32 v47, 0xffff0000, v47
	v_mul_f32_e32 v68, v60, v60
	v_mul_f32_e32 v70, v46, v46
	v_mov_b32_e32 v72, v54
	v_pk_fma_f32 v[66:67], v[58:59], v[58:59], v[66:67]
	v_mov_b32_e32 v55, v63
	v_mov_b32_e32 v73, v65
	v_and_b32_e32 v45, 0xffff0000, v48
	v_lshlrev_b32_e32 v48, 16, v49
	v_and_b32_e32 v49, 0xffff0000, v49
	v_pk_fma_f32 v[68:69], v[60:61], v[60:61], v[68:69] op_sel_hi:[1,1,0]
	v_pk_fma_f32 v[70:71], v[46:47], v[46:47], v[70:71] op_sel_hi:[1,1,0]
	v_pk_add_f32 v[66:67], v[66:67], v[66:67] op_sel_hi:[0,1]
	v_pk_add_f32 v[62:63], v[62:63], v[64:65]
	v_pk_mul_f32 v[64:65], v[54:55], v[72:73]
	v_mul_f32_e32 v68, v48, v48
	v_mul_f32_e32 v70, v49, v49
	v_mul_f32_e32 v66, v45, v45
	v_mov_b32_e32 v65, v63
	v_pk_add_f32 v[68:69], v[68:69], v[70:71]
	v_pk_add_f32 v[62:63], v[64:65], v[66:67]
	v_mov_b32_e32 v64, v58
	v_pk_add_f32 v[62:63], v[62:63], v[68:69]
	s_nop 0
	v_add_f32_e32 v55, v62, v63
	ds_bpermute_b32 v62, v17, v55
	s_waitcnt lgkmcnt(0)
	v_add_f32_e32 v55, v55, v62
	ds_bpermute_b32 v62, v38, v55
	s_waitcnt lgkmcnt(0)
	v_add_f32_e32 v55, v55, v62
	ds_bpermute_b32 v62, v39, v55
	s_waitcnt lgkmcnt(0)
	v_add_f32_e32 v55, v55, v62
	ds_bpermute_b32 v62, v40, v55
	s_waitcnt lgkmcnt(0)
	v_add_f32_e32 v55, v55, v62
	ds_bpermute_b32 v62, v41, v55
	s_waitcnt lgkmcnt(0)
	v_add_f32_e32 v55, v55, v62
	ds_bpermute_b32 v65, v42, v55
	v_lshl_add_u64 v[62:63], v[18:19], 0, s[6:7]
	s_waitcnt lgkmcnt(0)
	v_add_f32_e32 v55, v55, v65
	v_fmamk_f32 v55, v55, 0x3a800000, v44
	v_mul_f32_e32 v58, 0x4b800000, v55
	v_cmp_gt_f32_e32 vcc, s15, v55
	v_mov_b32_e32 v65, v52
	v_mov_b32_e32 v52, v59
	v_cndmask_b32_e32 v55, v55, v58, vcc
	v_rsq_f32_e32 v58, v55
	v_mov_b32_e32 v55, v45
	v_mul_f32_e32 v45, 0x45800000, v58
	v_cndmask_b32_e32 v58, v58, v45, vcc
	v_pk_mul_f32 v[56:57], v[58:59], v[56:57] op_sel_hi:[0,1]
	v_pk_mul_f32 v[50:51], v[58:59], v[50:51] op_sel_hi:[0,1]
	v_pk_mul_f32 v[64:65], v[58:59], v[64:65] op_sel_hi:[0,1]
	v_pk_mul_f32 v[52:53], v[58:59], v[52:53] op_sel_hi:[0,1]
	v_pk_mul_f32 v[46:47], v[58:59], v[46:47] op_sel_hi:[0,1]
	v_pk_mul_f32 v[48:49], v[48:49], v[58:59] op_sel_hi:[1,0]
	v_pk_mul_f32 v[60:61], v[58:59], v[60:61] op_sel_hi:[0,1]
	v_pk_mul_f32 v[54:55], v[54:55], v[58:59] op_sel_hi:[1,0]
	v_pk_fma_f32 v[50:51], v[24:25], v[50:51], v[14:15]
	v_pk_fma_f32 v[56:57], v[22:23], v[56:57], v[12:13]
	v_pk_fma_f32 v[52:53], v[26:27], v[52:53], v[6:7]
	v_pk_fma_f32 v[58:59], v[32:33], v[64:65], v[4:5]
	v_pk_fma_f32 v[64:65], v[28:29], v[46:47], v[10:11]
	v_pk_fma_f32 v[66:67], v[30:31], v[48:49], v[2:3]
	v_cvt_pk_bf16_f32 v46, v56, v57
	v_cvt_pk_bf16_f32 v47, v50, v51
	v_cvt_pk_bf16_f32 v48, v58, v59
	v_cvt_pk_bf16_f32 v49, v52, v53
	v_pk_fma_f32 v[60:61], v[34:35], v[60:61], v[8:9]
	v_pk_fma_f32 v[54:55], v[36:37], v[54:55], v[0:1]
	v_mov_b32_e32 v204, v46
	v_mov_b32_e32 v205, v47
	v_mov_b32_e32 v206, v48
	v_mov_b32_e32 v207, v49
	v_mov_b32_e32 v212, v62
	v_mov_b32_e32 v213, v63
	s_nop 1
	v_cvt_pk_bf16_f32 v46, v60, v61
	v_cvt_pk_bf16_f32 v47, v64, v65
	v_cvt_pk_bf16_f32 v48, v54, v55
	v_cvt_pk_bf16_f32 v49, v66, v67
	v_mov_b32_e32 v208, v46
	v_mov_b32_e32 v209, v47
	v_mov_b32_e32 v210, v48
	v_mov_b32_e32 v211, v49
	s_mov_b32 s100, 1
	s_cbranch_scc0 .LBB0_745

; __device__ __forceinline__ unsigned cvt_pk_bf16(float lo, float hi) { unsigned r; asm volatile("v_cvt_pk_bf16_f32 %0, %1, %2" : "=v"(r) : "v"(lo), "v"(hi)); return r; }
; __device__ __forceinline__ void ld8(const bf16_t* p, f32x4& a, f32x4& b) { const u32x4 r = *(const u32x4*)p;
;     a = (f32x4){__uint_as_float(r.x << 16), __uint_as_float(r.x & 0xffff0000u), __uint_as_float(r.y << 16), __uint_as_float(r.y & 0xffff0000u)};
;     b = (f32x4){__uint_as_float(r.z << 16), __uint_as_float(r.z & 0xffff0000u), __uint_as_float(r.w << 16), __uint_as_float(r.w & 0xffff0000u)}; }
; __device__ __forceinline__ void st8(bf16_t* p, f32x4 a, f32x4 b) { u32x4 w; w.x = cvt_pk_bf16(a[0], a[1]); w.y = cvt_pk_bf16(a[2], a[3]); w.z = cvt_pk_bf16(b[0], b[1]); w.w = cvt_pk_bf16(b[2], b[3]); *(u32x4*)p = w; }
; template <class T>
; __device__ __forceinline__ void phase_norm(const T* xl, const T* xc, const float* nw, const float* mod  , int sh_off, int sc_off,
;                                            bf16u* HN, int skip_ctx, int lane, int wave, int G, const int bid) {
;     ...
;     for (int m = gw; m < MROWS; m += NGW) {
;         const int b = m / SEQU, j = m % SEQU; const bool isc = j < CTXL; if (isc && skip_ctx) continue;
;         const int wh = isc ? 2 : b; const T* src = isc ? xc + (size_t)(b * CTXL + j) * DM : xl + (size_t)(b * LSEQ + j - CTXL) * DM;
;         if (wh != cur) { cur = wh;
; #pragma unroll
;             for (int jj = 0; jj < 4; ++jj) { const int k = 8 * lane + 4 * (jj & 1) + 512 * (jj >> 1); const f32x4 w = *(const f32x4*)(nw + k), sc = *(const f32x4*)(mod + wh * NMODV + sc_off + k);
;                 a[jj] = w * (sc + 1.0f); s[jj] = *(const f32x4*)(mod + wh * NMODV + sh_off + k); } }
;         f32x4 v[4]; float ss = 0.f;
; #pragma unroll
;         for (int h = 0; h < 2; ++h) pg8::ld8(src + 8 * lane + 512 * h, v[2 * h], v[2 * h + 1]);
; #pragma unroll
;         for (int jj = 0; jj < 4; ++jj) ss += (v[jj].x * v[jj].x + v[jj].y * v[jj].y) + (v[jj].z * v[jj].z + v[jj].w * v[jj].w);
;         const float rstd = rsqrtf(wave_sum(ss, lane) * (1.0f / DM) + EPSN);
; #pragma unroll
;         for (int h = 0; h < 2; ++h) pg8::st8(HN + (size_t)m * DM + 8 * lane + 512 * h, (v[2 * h] * rstd) * a[2 * h] + s[2 * h], (v[2 * h + 1] * rstd) * a[2 * h + 1] + s[2 * h + 1]);
;     }
.LBB0_1050:
	s_mov_b32 s100, 0
	s_cmp_lt_i32 s70, 12
	s_cselect_b64 s[2:3], -1, 0
	s_and_b64 s[2:3], s[2:3], s[0:1]
	s_andn2_b64 vcc, exec, s[2:3]
	s_cbranch_vccnz .LBB0_1060
	s_mov_b32 s0, 0
	s_add_i32 s1, 0, 0x24820
	s_waitcnt vmcnt(0)
	v_mbcnt_lo_u32_b32 v0, -1, s0
	v_mbcnt_hi_u32_b32 v0, -1, v0
	v_add_u32_e32 v0, s86, v0
	s_mov_b32 s0, s83
	s_mov_b32 s5, s84
	v_mov_b32_e32 v1, s1
	s_add_i32 s1, 0, 0x248c0
	ds_read_b64 v[2:3], v1
	v_mov_b32_e32 v1, s1
	ds_read_b64 v[4:5], v1
	v_readfirstlane_b32 s1, v0
	s_ashr_i32 s4, s1, 6
	s_lshl_b32 s0, s0, 3
	s_add_i32 s4, s4, s0
	s_mov_b32 s16, -1
	s_waitcnt lgkmcnt(1)
	v_readfirstlane_b32 s6, v3
	v_readfirstlane_b32 s7, v2
	s_waitcnt lgkmcnt(0)
	v_readfirstlane_b32 s1, v5
	s_cmp_gt_i32 s4, 0x81ff
	v_readfirstlane_b32 s0, v4
	s_cbranch_scc1 .LBB0_1060
	s_add_u32 s12, s0, 0x3012000
	s_addc_u32 s13, s1, 0
	s_lshl_b32 s14, s5, 3
	v_and_b32_e32 v2, 63, v0
	s_add_u32 s8, s7, 0x1000
	v_mov_b32_e32 v25, 0
	v_lshlrev_b32_e32 v0, 2, v2
	v_lshlrev_b32_e32 v24, 4, v2
	s_addc_u32 s9, s6, 0
	v_lshlrev_b32_e32 v16, 3, v2
	v_xor_b32_e32 v17, 4, v0
	v_xor_b32_e32 v40, 8, v0
	v_xor_b32_e32 v41, 16, v0
	v_xor_b32_e32 v42, 32, v0
	v_xor_b32_e32 v43, 64, v0
	v_xor_b32_e32 v44, 0x80, v0
	v_lshl_add_u64 v[0:1], s[0:1], 0, v[24:25]
	s_mov_b64 s[6:7], 0x3500000
	v_lshl_add_u64 v[18:19], v[0:1], 0, s[6:7]
	v_lshlrev_b32_e32 v24, 5, v2
	v_or_b32_e32 v0, 0x200, v16
	v_lshl_add_u64 v[20:21], s[8:9], 0, v[24:25]
	v_lshlrev_b32_e32 v24, 2, v0
	v_lshl_add_u64 v[22:23], s[8:9], 0, v[24:25]
	v_mov_b32_e32 v24, v25
	v_mov_b32_e32 v26, v25
	v_mov_b32_e32 v27, v25
	v_mov_b32_e32 v34, v25
	v_mov_b32_e32 v35, v25
	v_mov_b32_e32 v28, v25
	v_mov_b32_e32 v29, v25
	v_mov_b32_e32 v36, v25
	v_mov_b32_e32 v37, v25
	v_mov_b32_e32 v30, v25
	v_mov_b32_e32 v31, v25
	v_mov_b32_e32 v38, v25
	v_mov_b32_e32 v39, v25
	v_mov_b32_e32 v32, v25
	v_mov_b32_e32 v33, v25
	v_lshlrev_b32_e32 v45, 2, v0
	v_mov_b32_e32 v46, 0x358637bd
	s_mov_b32 s15, 0x800000
	s_branch .LBB0_1054
.LBB0_1053:
	s_add_u32 s5, s0, s8
	s_addc_u32 s8, s1, s9
	s_ashr_i32 s7, s6, 31
	s_lshl_b64 s[6:7], s[6:7], 11
	s_add_u32 s6, s5, s6
	s_addc_u32 s7, s8, s7
	v_lshlrev_b32_e32 v47, 1, v16
	global_load_dwordx4 v[48:51], v47, s[6:7] offset:1024
	global_load_dwordx4 v[52:55], v47, s[6:7]
	s_lshl_b32 s98, s14, 11
	s_add_u32 s98, s6, s98
	s_addc_u32 s99, s7, 0
	s_cmp_eq_u32 s100, 0
	s_cbranch_scc1 .Lnorm11_first
	global_store_dwordx4 v[212:213], v[204:207], off
	global_store_dwordx4 v[212:213], v[208:211], off offset:1024
	s_branch .Lnorm11_join
.Lnorm11_first:
	global_load_dword v200, v47, s[6:7]
	global_load_dword v200, v47, s[6:7] offset:1024
.Lnorm11_join:
	global_load_dword v200, v47, s[98:99] offset:1024
	global_load_dword v200, v47, s[98:99]
	s_ashr_i32 s5, s4, 31
	s_lshl_b64 s[6:7], s[4:5], 11
	s_add_i32 s4, s4, s14
	s_cmp_lt_i32 s4, 0x8200
	s_waitcnt vmcnt(5)
	v_lshlrev_b32_e32 v56, 16, v50
	s_waitcnt vmcnt(4)
	v_lshlrev_b32_e32 v58, 16, v52
	v_and_b32_e32 v59, 0xffff0000, v52
	v_lshlrev_b32_e32 v52, 16, v53
	v_and_b32_e32 v53, 0xffff0000, v53
	v_lshlrev_b32_e32 v61, 16, v55
	v_lshlrev_b32_e32 v60, 16, v54
	v_and_b32_e32 v55, 0xffff0000, v55
	v_and_b32_e32 v54, 0xffff0000, v54
	v_mul_f32_e32 v64, v58, v58
	v_mul_f32_e32 v66, v52, v52
	v_lshlrev_b32_e32 v62, 16, v48
	v_and_b32_e32 v63, 0xffff0000, v48
	v_lshlrev_b32_e32 v48, 16, v49
	v_pk_mul_f32 v[68:69], v[54:55], v[54:55]
	v_pk_fma_f32 v[64:65], v[58:59], v[58:59], v[64:65] op_sel_hi:[1,1,0]
	v_pk_fma_f32 v[66:67], v[52:53], v[52:53], v[66:67] op_sel_hi:[1,1,0]
	v_and_b32_e32 v49, 0xffff0000, v49
	v_mul_f32_e32 v70, v62, v62
	v_mul_f32_e32 v72, v48, v48
	v_mov_b32_e32 v74, v56
	v_pk_fma_f32 v[68:69], v[60:61], v[60:61], v[68:69]
	v_mov_b32_e32 v57, v65
	v_mov_b32_e32 v75, v67
	v_and_b32_e32 v47, 0xffff0000, v50
	v_lshlrev_b32_e32 v50, 16, v51
	v_and_b32_e32 v51, 0xffff0000, v51
	v_pk_fma_f32 v[70:71], v[62:63], v[62:63], v[70:71] op_sel_hi:[1,1,0]
	v_pk_fma_f32 v[72:73], v[48:49], v[48:49], v[72:73] op_sel_hi:[1,1,0]
	v_pk_add_f32 v[68:69], v[68:69], v[68:69] op_sel_hi:[0,1]
	v_pk_add_f32 v[64:65], v[64:65], v[66:67]
	v_pk_mul_f32 v[66:67], v[56:57], v[74:75]
	v_mul_f32_e32 v70, v50, v50
	v_mul_f32_e32 v72, v51, v51
	v_mul_f32_e32 v68, v47, v47
	v_mov_b32_e32 v67, v65
	v_pk_add_f32 v[70:71], v[70:71], v[72:73]
	v_pk_add_f32 v[64:65], v[66:67], v[68:69]
	v_mov_b32_e32 v66, v60
	v_pk_add_f32 v[64:65], v[64:65], v[70:71]
	s_nop 0
	v_add_f32_e32 v57, v64, v65
	ds_bpermute_b32 v64, v17, v57
	s_waitcnt lgkmcnt(0)
	v_add_f32_e32 v57, v57, v64
	ds_bpermute_b32 v64, v40, v57
	s_waitcnt lgkmcnt(0)
	v_add_f32_e32 v57, v57, v64
	ds_bpermute_b32 v64, v41, v57
	s_waitcnt lgkmcnt(0)
	v_add_f32_e32 v57, v57, v64
	ds_bpermute_b32 v64, v42, v57
	s_waitcnt lgkmcnt(0)
	v_add_f32_e32 v57, v57, v64
	ds_bpermute_b32 v64, v43, v57
	s_waitcnt lgkmcnt(0)
	v_add_f32_e32 v57, v57, v64
	ds_bpermute_b32 v67, v44, v57
	v_lshl_add_u64 v[64:65], v[18:19], 0, s[6:7]
	s_waitcnt lgkmcnt(0)
	v_add_f32_e32 v57, v57, v67
	v_fmamk_f32 v57, v57, 0x3a800000, v46
	v_mul_f32_e32 v60, 0x4b800000, v57
	v_cmp_gt_f32_e32 vcc, s15, v57
	v_mov_b32_e32 v67, v54
	v_mov_b32_e32 v54, v61
	v_cndmask_b32_e32 v57, v57, v60, vcc
	v_rsq_f32_e32 v60, v57
	v_mov_b32_e32 v57, v47
	v_mul_f32_e32 v47, 0x45800000, v60
	v_cndmask_b32_e32 v60, v60, v47, vcc
	v_pk_mul_f32 v[58:59], v[60:61], v[58:59] op_sel_hi:[0,1]
	v_pk_mul_f32 v[52:53], v[60:61], v[52:53] op_sel_hi:[0,1]
	v_pk_mul_f32 v[66:67], v[60:61], v[66:67] op_sel_hi:[0,1]
	v_pk_mul_f32 v[54:55], v[60:61], v[54:55] op_sel_hi:[0,1]
	v_pk_mul_f32 v[48:49], v[60:61], v[48:49] op_sel_hi:[0,1]
	v_pk_mul_f32 v[50:51], v[50:51], v[60:61] op_sel_hi:[1,0]
	v_pk_mul_f32 v[62:63], v[60:61], v[62:63] op_sel_hi:[0,1]
	v_pk_mul_f32 v[56:57], v[56:57], v[60:61] op_sel_hi:[1,0]
	v_pk_fma_f32 v[52:53], v[26:27], v[52:53], v[14:15]
	v_pk_fma_f32 v[58:59], v[24:25], v[58:59], v[12:13]
	v_pk_fma_f32 v[54:55], v[28:29], v[54:55], v[6:7]
	v_pk_fma_f32 v[60:61], v[34:35], v[66:67], v[4:5]
	v_pk_fma_f32 v[66:67], v[30:31], v[48:49], v[10:11]
	v_pk_fma_f32 v[68:69], v[32:33], v[50:51], v[2:3]
	v_cvt_pk_bf16_f32 v48, v58, v59
	v_cvt_pk_bf16_f32 v49, v52, v53
	v_cvt_pk_bf16_f32 v50, v60, v61
	v_cvt_pk_bf16_f32 v51, v54, v55
	v_pk_fma_f32 v[62:63], v[36:37], v[62:63], v[8:9]
	v_pk_fma_f32 v[56:57], v[38:39], v[56:57], v[0:1]
	v_mov_b32_e32 v204, v48
	v_mov_b32_e32 v205, v49
	v_mov_b32_e32 v206, v50
	v_mov_b32_e32 v207, v51
	v_mov_b32_e32 v212, v64
	v_mov_b32_e32 v213, v65
	s_nop 1
	v_cvt_pk_bf16_f32 v48, v62, v63
	v_cvt_pk_bf16_f32 v49, v66, v67
	v_cvt_pk_bf16_f32 v50, v56, v57
	v_cvt_pk_bf16_f32 v51, v68, v69
	v_mov_b32_e32 v208, v48
	v_mov_b32_e32 v209, v49
	v_mov_b32_e32 v210, v50
	v_mov_b32_e32 v211, v51
	s_mov_b32 s100, 1
	s_cbranch_scc0 .LBB0_1060

; __device__ __forceinline__ unsigned cvt_pk_bf16(float lo, float hi) { unsigned r; asm volatile("v_cvt_pk_bf16_f32 %0, %1, %2" : "=v"(r) : "v"(lo), "v"(hi)); return r; }
; __device__ __forceinline__ void ld8(const bf16_t* p, f32x4& a, f32x4& b) { const u32x4 r = *(const u32x4*)p;
;     a = (f32x4){__uint_as_float(r.x << 16), __uint_as_float(r.x & 0xffff0000u), __uint_as_float(r.y << 16), __uint_as_float(r.y & 0xffff0000u)};
;     b = (f32x4){__uint_as_float(r.z << 16), __uint_as_float(r.z & 0xffff0000u), __uint_as_float(r.w << 16), __uint_as_float(r.w & 0xffff0000u)}; }
; __device__ __forceinline__ void st8(bf16_t* p, f32x4 a, f32x4 b) { u32x4 w; w.x = cvt_pk_bf16(a[0], a[1]); w.y = cvt_pk_bf16(a[2], a[3]); w.z = cvt_pk_bf16(b[0], b[1]); w.w = cvt_pk_bf16(b[2], b[3]); *(u32x4*)p = w; }
; template <class T>
; __device__ __forceinline__ void phase_norm(const T* xl, const T* xc, const float* nw, const float* mod  , int sh_off, int sc_off,
;                                            bf16u* HN, int skip_ctx, int lane, int wave, int G, const int bid) {
;     ...
;     for (int m = gw; m < MROWS; m += NGW) {
;         const int b = m / SEQU, j = m % SEQU; const bool isc = j < CTXL; if (isc && skip_ctx) continue;
;         const int wh = isc ? 2 : b; const T* src = isc ? xc + (size_t)(b * CTXL + j) * DM : xl + (size_t)(b * LSEQ + j - CTXL) * DM;
;         if (wh != cur) { cur = wh;
; #pragma unroll
;             for (int jj = 0; jj < 4; ++jj) { const int k = 8 * lane + 4 * (jj & 1) + 512 * (jj >> 1); const f32x4 w = *(const f32x4*)(nw + k), sc = *(const f32x4*)(mod + wh * NMODV + sc_off + k);
;                 a[jj] = w * (sc + 1.0f); s[jj] = *(const f32x4*)(mod + wh * NMODV + sh_off + k); } }
;         f32x4 v[4]; float ss = 0.f;
; #pragma unroll
;         for (int h = 0; h < 2; ++h) pg8::ld8(src + 8 * lane + 512 * h, v[2 * h], v[2 * h + 1]);
; #pragma unroll
;         for (int jj = 0; jj < 4; ++jj) ss += (v[jj].x * v[jj].x + v[jj].y * v[jj].y) + (v[jj].z * v[jj].z + v[jj].w * v[jj].w);
;         const float rstd = rsqrtf(wave_sum(ss, lane) * (1.0f / DM) + EPSN);
; #pragma unroll
;         for (int h = 0; h < 2; ++h) pg8::st8(HN + (size_t)m * DM + 8 * lane + 512 * h, (v[2 * h] * rstd) * a[2 * h] + s[2 * h], (v[2 * h + 1] * rstd) * a[2 * h + 1] + s[2 * h + 1]);
;     }
.LBB0_1636:
	s_mov_b32 s100, 0
	s_cmp_lt_i32 s70, 18
	s_cselect_b64 s[2:3], -1, 0
	s_and_b64 s[2:3], s[2:3], s[0:1]
	s_andn2_b64 vcc, exec, s[2:3]
	s_cbranch_vccnz .LBB0_1644
	s_mov_b32 s0, 0
	s_add_i32 s4, 0, 0x24828
	s_waitcnt vmcnt(0)
	v_mbcnt_lo_u32_b32 v0, -1, s0
	v_mbcnt_hi_u32_b32 v0, -1, v0
	v_add_u32_e32 v0, s62, v0
	s_mov_b32 s0, s61
	s_mov_b32 s1, s84
	v_mov_b32_e32 v1, s4
	s_add_i32 s4, 0, 0x248c0
	ds_read_b64 v[2:3], v1
	v_mov_b32_e32 v1, s4
	ds_read_b64 v[4:5], v1
	v_readfirstlane_b32 s4, v0
	s_ashr_i32 s4, s4, 6
	s_lshl_b32 s0, s0, 3
	s_add_i32 s0, s4, s0
	s_mov_b32 s9, -1
	s_waitcnt lgkmcnt(1)
	v_readfirstlane_b32 s10, v3
	v_readfirstlane_b32 s11, v2
	s_waitcnt lgkmcnt(0)
	v_readfirstlane_b32 s5, v5
	s_cmp_gt_i32 s0, 0x81ff
	v_readfirstlane_b32 s4, v4
	s_cbranch_scc1 .LBB0_1644
	s_add_u32 s6, s4, 0x3012000
	s_addc_u32 s7, s5, 0
	s_lshl_b32 s8, s1, 3
	v_and_b32_e32 v1, 63, v0
	s_add_u32 s12, s11, 0x1000
	v_lshlrev_b32_e32 v0, 3, v1
	v_mov_b32_e32 v25, 0
	v_lshlrev_b32_e32 v2, 2, v1
	v_lshlrev_b32_e32 v24, 4, v1
	s_addc_u32 s13, s10, 0
	v_xor_b32_e32 v40, 4, v2
	v_xor_b32_e32 v41, 8, v2
	v_xor_b32_e32 v42, 16, v2
	v_xor_b32_e32 v43, 32, v2
	v_xor_b32_e32 v44, 64, v2
	v_xor_b32_e32 v45, 0x80, v2
	v_lshl_add_u64 v[2:3], s[4:5], 0, v[24:25]
	s_mov_b64 s[4:5], 0x3500000
	v_lshlrev_b32_e32 v24, 5, v1
	v_or_b32_e32 v4, 0x200, v0
	v_lshl_add_u64 v[16:17], v[2:3], 0, s[4:5]
	v_lshl_add_u64 v[18:19], s[12:13], 0, v[24:25]
	v_lshlrev_b32_e32 v24, 2, v4
	s_mov_b64 s[4:5], 0x8800000
	v_lshl_add_u64 v[20:21], s[12:13], 0, v[24:25]
	v_lshl_add_u64 v[22:23], v[2:3], 0, s[4:5]
	v_mov_b32_e32 v24, v25
	v_mov_b32_e32 v26, v25
	v_mov_b32_e32 v27, v25
	v_mov_b32_e32 v34, v25
	v_mov_b32_e32 v35, v25
	v_mov_b32_e32 v28, v25
	v_mov_b32_e32 v29, v25
	v_mov_b32_e32 v36, v25
	v_mov_b32_e32 v37, v25
	v_mov_b32_e32 v30, v25
	v_mov_b32_e32 v31, v25
	v_mov_b32_e32 v38, v25
	v_mov_b32_e32 v39, v25
	v_mov_b32_e32 v32, v25
	v_mov_b32_e32 v33, v25
	v_lshlrev_b32_e32 v46, 2, v0
	v_lshlrev_b32_e32 v47, 2, v4
	v_mov_b32_e32 v48, 0x358637bd
	s_mov_b32 s4, 0x800000
	s_branch .LBB0_1641
.LBB0_1639:
	s_lshl_b32 s1, s1, 8
	s_sub_i32 s1, s0, s1
	s_add_i32 s10, s1, 0xffffff00
	s_ashr_i32 s11, s10, 31
	s_lshl_b64 s[10:11], s[10:11], 11
	v_lshl_add_u64 v[58:59], v[22:23], 0, s[10:11]
	global_load_dwordx4 v[50:53], v[58:59], off offset:1024
	global_load_dwordx4 v[54:57], v[58:59], off
	s_lshl_b32 s98, s8, 11
	s_mov_b32 s99, 0
	v_lshl_add_u64 v[200:201], v[58:59], 0, s[98:99]
	s_cmp_eq_u32 s100, 0
	s_cbranch_scc1 .Lnorm17_first
	global_store_dwordx4 v[212:213], v[204:207], off
	global_store_dwordx4 v[212:213], v[208:211], off offset:1024
	s_branch .Lnorm17_join
.Lnorm17_first:
	global_load_dword v202, v[58:59], off
	global_load_dword v202, v[58:59], off offset:1024
.Lnorm17_join:
	global_load_dword v202, v[200:201], off offset:1024
	global_load_dword v202, v[200:201], off
	s_ashr_i32 s1, s0, 31
	s_lshl_b64 s[10:11], s[0:1], 11
	s_waitcnt vmcnt(5)
	v_lshlrev_b32_e32 v58, 16, v52
	s_waitcnt vmcnt(4)
	v_lshlrev_b32_e32 v60, 16, v54
	v_and_b32_e32 v61, 0xffff0000, v54
	v_lshlrev_b32_e32 v54, 16, v55
	v_and_b32_e32 v55, 0xffff0000, v55
	v_lshlrev_b32_e32 v63, 16, v57
	v_lshlrev_b32_e32 v62, 16, v56
	v_and_b32_e32 v57, 0xffff0000, v57
	v_and_b32_e32 v56, 0xffff0000, v56
	v_mul_f32_e32 v66, v60, v60
	v_mul_f32_e32 v68, v54, v54
	v_lshlrev_b32_e32 v64, 16, v50
	v_and_b32_e32 v65, 0xffff0000, v50
	v_lshlrev_b32_e32 v50, 16, v51
	v_pk_mul_f32 v[70:71], v[56:57], v[56:57]
	v_pk_fma_f32 v[66:67], v[60:61], v[60:61], v[66:67] op_sel_hi:[1,1,0]
	v_pk_fma_f32 v[68:69], v[54:55], v[54:55], v[68:69] op_sel_hi:[1,1,0]
	v_and_b32_e32 v51, 0xffff0000, v51
	v_mul_f32_e32 v72, v64, v64
	v_mul_f32_e32 v74, v50, v50
	v_mov_b32_e32 v76, v58
	v_pk_fma_f32 v[70:71], v[62:63], v[62:63], v[70:71]
	v_mov_b32_e32 v59, v67
	v_mov_b32_e32 v77, v69
	v_and_b32_e32 v49, 0xffff0000, v52
	v_lshlrev_b32_e32 v52, 16, v53
	v_and_b32_e32 v53, 0xffff0000, v53
	v_pk_fma_f32 v[72:73], v[64:65], v[64:65], v[72:73] op_sel_hi:[1,1,0]
	v_pk_fma_f32 v[74:75], v[50:51], v[50:51], v[74:75] op_sel_hi:[1,1,0]
	v_pk_add_f32 v[70:71], v[70:71], v[70:71] op_sel_hi:[0,1]
	v_pk_add_f32 v[66:67], v[66:67], v[68:69]
	v_pk_mul_f32 v[68:69], v[58:59], v[76:77]
	v_mul_f32_e32 v72, v52, v52
	v_mul_f32_e32 v74, v53, v53
	v_mul_f32_e32 v70, v49, v49
	v_mov_b32_e32 v69, v67
	v_pk_add_f32 v[72:73], v[72:73], v[74:75]
	v_pk_add_f32 v[66:67], v[68:69], v[70:71]
	v_mov_b32_e32 v68, v62
	v_pk_add_f32 v[66:67], v[66:67], v[72:73]
	s_nop 0
	v_add_f32_e32 v59, v66, v67
	ds_bpermute_b32 v66, v40, v59
	s_waitcnt lgkmcnt(0)
	v_add_f32_e32 v59, v59, v66
	ds_bpermute_b32 v66, v41, v59
	s_waitcnt lgkmcnt(0)
	v_add_f32_e32 v59, v59, v66
	ds_bpermute_b32 v66, v42, v59
	s_waitcnt lgkmcnt(0)
	v_add_f32_e32 v59, v59, v66
	ds_bpermute_b32 v66, v43, v59
	s_waitcnt lgkmcnt(0)
	v_add_f32_e32 v59, v59, v66
	ds_bpermute_b32 v66, v44, v59
	s_waitcnt lgkmcnt(0)
	v_add_f32_e32 v59, v59, v66
	ds_bpermute_b32 v69, v45, v59
	v_lshl_add_u64 v[66:67], v[16:17], 0, s[10:11]
	s_waitcnt lgkmcnt(0)
	v_add_f32_e32 v59, v59, v69
	v_fmamk_f32 v59, v59, 0x3a800000, v48
	v_mul_f32_e32 v62, 0x4b800000, v59
	v_cmp_gt_f32_e32 vcc, s4, v59
	v_mov_b32_e32 v69, v56
	v_mov_b32_e32 v56, v63
	v_cndmask_b32_e32 v59, v59, v62, vcc
	v_rsq_f32_e32 v62, v59
	v_mov_b32_e32 v59, v49
	v_mul_f32_e32 v49, 0x45800000, v62
	v_cndmask_b32_e32 v62, v62, v49, vcc
	v_pk_mul_f32 v[60:61], v[62:63], v[60:61] op_sel_hi:[0,1]
	v_pk_mul_f32 v[54:55], v[62:63], v[54:55] op_sel_hi:[0,1]
	v_pk_mul_f32 v[68:69], v[62:63], v[68:69] op_sel_hi:[0,1]
	v_pk_mul_f32 v[56:57], v[62:63], v[56:57] op_sel_hi:[0,1]
	v_pk_mul_f32 v[50:51], v[62:63], v[50:51] op_sel_hi:[0,1]
	v_pk_mul_f32 v[52:53], v[52:53], v[62:63] op_sel_hi:[1,0]
	v_pk_mul_f32 v[64:65], v[62:63], v[64:65] op_sel_hi:[0,1]
	v_pk_mul_f32 v[58:59], v[58:59], v[62:63] op_sel_hi:[1,0]
	v_pk_fma_f32 v[54:55], v[26:27], v[54:55], v[14:15]
	v_pk_fma_f32 v[60:61], v[24:25], v[60:61], v[12:13]
	v_pk_fma_f32 v[56:57], v[28:29], v[56:57], v[6:7]
	v_pk_fma_f32 v[62:63], v[34:35], v[68:69], v[4:5]
	v_pk_fma_f32 v[68:69], v[30:31], v[50:51], v[10:11]
	v_pk_fma_f32 v[70:71], v[32:33], v[52:53], v[2:3]
	v_cvt_pk_bf16_f32 v50, v60, v61
	v_cvt_pk_bf16_f32 v51, v54, v55
	v_cvt_pk_bf16_f32 v52, v62, v63
	v_cvt_pk_bf16_f32 v53, v56, v57
	v_pk_fma_f32 v[64:65], v[36:37], v[64:65], v[8:9]
	v_pk_fma_f32 v[58:59], v[38:39], v[58:59], v[0:1]
	v_mov_b32_e32 v204, v50
	v_mov_b32_e32 v205, v51
	v_mov_b32_e32 v206, v52
	v_mov_b32_e32 v207, v53
	v_mov_b32_e32 v212, v66
	v_mov_b32_e32 v213, v67
	s_nop 1
	v_cvt_pk_bf16_f32 v50, v64, v65
	v_cvt_pk_bf16_f32 v51, v68, v69
	v_cvt_pk_bf16_f32 v52, v58, v59
	v_cvt_pk_bf16_f32 v53, v70, v71
	v_mov_b32_e32 v208, v50
	v_mov_b32_e32 v209, v51
	v_mov_b32_e32 v210, v52
	v_mov_b32_e32 v211, v53
	s_mov_b32 s100, 1
